# c2 + exact counted vmcnt waits in P5 indexer tile loop (16 key-fragment loads kept in flight)
# speedup vs baseline: 1.0113x; 1.0004x over previous
; #define IDX_LOAD(BUF, tl) do { const int tc_ = (tl) < 64 ? (tl) : 64; const unsigned char* bp_ = ws + WS_KI2 + ((size_t)b * 65 + tc_) * 4096 + (hh * 32 + lr) * 16; \
;                 _Pragma("unroll") for (int kk = 0; kk < 4; ++kk) BUF[kk] = *(const bf16x8*)(bp_ + kk * 1024); } while (0)
; __device__ __forceinline__ void phase_attn(const Params& P, unsigned char* lds) {
;     ...
;             const int p = wave * 2 + pp; const int sq = s0 + 2 * p + hh; const int rowq = b * SEQ + sq;
;             bf16x8 Aq[4];
;             { const int qa = s0 + 2 * p + ((lr >> 2) & 1), ha = (lr & 3) + 4 * (lr >> 3);
;               const bf16_t* ap = Z1 + (size_t)(b * SEQ + qa) * LDZ + 1536 + ha * 64 + hh * 32;
; #pragma unroll
;               for (int kk = 0; kk < 4; ++kk) Aq[kk] = *(const bf16x8*)(ap + kk * 8); }
;             float wv[16];
;             { float a[8], c[8]; unpack8(*(const u32x4*)(Z1 + (size_t)rowq * LDZ + 2624), a); unpack8(*(const u32x4*)(Z1 + (size_t)rowq * LDZ + 2632), c);
; #pragma unroll
;               for (int i = 0; i < 8; ++i) { wv[i] = a[i]; wv[8 + i] = c[i]; } }
;             unsigned* myrow = scU + (wave * 2 + hh) * TPAD + lr;
;             bf16x8 B0[4], B1[4], B2[4], B3[4];
;     ...
;             IDX_LOAD(B0, 0); IDX_LOAD(B1, 1); IDX_LOAD(B2, 2); IDX_LOAD(B3, 3);
.LBB0_623:
	v_or_b32_e32 v2, s6, v201
	v_lshlrev_b32_e32 v183, 1, v2
	v_add_u32_e32 v10, s75, v183
	v_or_b32_e32 v12, v10, v200
	v_add_u32_e32 v4, s73, v12
	v_mov_b64_e32 v[2:3], s[44:45]
	v_mad_u64_u32 v[6:7], s[6:7], v4, s34, v[2:3]
	v_add_co_u32_e32 v2, vcc, s23, v6
	s_mov_b64 s[6:7], 0x1480
	v_add_u32_e32 v10, v0, v10
	v_addc_co_u32_e32 v3, vcc, 0, v7, vcc
	v_lshl_add_u64 v[6:7], v[6:7], 0, s[6:7]
	v_mad_u64_u32 v[10:11], s[6:7], v10, s34, v[176:177]
	global_load_dwordx4 v[2:5], v[2:3], off offset:1152
	s_waitcnt vmcnt(0)
	v_mov_b64_e32 v[100:101], v[36:37]
	global_load_dwordx4 v[6:9], v[6:7], off offset:16
	s_nop 0
	global_load_dwordx4 v[82:85], v[10:11], off offset:3072
	global_load_dwordx4 v[86:89], v[10:11], off offset:3088
	global_load_dwordx4 v[90:93], v[10:11], off offset:3104
	global_load_dwordx4 v[94:97], v[10:11], off offset:3120
	v_mov_b64_e32 v[108:109], v[40:41]
	v_mov_b64_e32 v[112:113], v[44:45]
	v_mov_b64_e32 v[120:121], v[60:61]
	v_mov_b64_e32 v[104:105], v[28:29]
	v_mov_b64_e32 v[124:125], v[20:21]
	v_mov_b64_e32 v[128:129], v[24:25]
	v_mov_b64_e32 v[132:133], v[32:33]
	v_mov_b64_e32 v[136:137], v[64:65]
	v_mov_b64_e32 v[140:141], v[56:57]
	v_mov_b64_e32 v[144:145], v[52:53]
	v_mov_b64_e32 v[116:117], v[48:49]
	v_mov_b64_e32 v[148:149], v[80:81]
	v_mov_b64_e32 v[152:153], v[76:77]
	v_mov_b64_e32 v[156:157], v[72:73]
	v_mov_b64_e32 v[160:161], v[68:69]
	s_xor_b64 s[68:69], s[0:1], -1
	s_mov_b32 s0, 0
	v_mov_b32_e32 v226, v163
	v_mov_b32_e32 v227, v204
	v_mov_b64_e32 v[98:99], v[34:35]
	v_mov_b64_e32 v[106:107], v[38:39]
	v_mov_b64_e32 v[110:111], v[42:43]
	v_mov_b64_e32 v[118:119], v[58:59]
	v_mov_b64_e32 v[102:103], v[26:27]
	v_mov_b64_e32 v[122:123], v[18:19]
	v_mov_b64_e32 v[126:127], v[22:23]
	v_mov_b64_e32 v[130:131], v[30:31]
	v_mov_b64_e32 v[134:135], v[62:63]
	v_mov_b64_e32 v[138:139], v[54:55]
	v_mov_b64_e32 v[142:143], v[50:51]
	v_mov_b64_e32 v[114:115], v[46:47]
	v_mov_b64_e32 v[146:147], v[78:79]
	v_mov_b64_e32 v[150:151], v[74:75]
	v_mov_b64_e32 v[154:155], v[70:71]
	v_add_u32_e32 v228, 16, v12
	v_mov_b64_e32 v[158:159], v[66:67]
	v_lshlrev_b32_e32 v184, 16, v2
	v_and_b32_e32 v185, 0xffff0000, v2
	v_lshlrev_b32_e32 v186, 16, v3
	v_and_b32_e32 v187, 0xffff0000, v3
	v_lshlrev_b32_e32 v188, 16, v4
	v_and_b32_e32 v189, 0xffff0000, v4
	v_lshlrev_b32_e32 v190, 16, v5
	v_and_b32_e32 v191, 0xffff0000, v5
	s_waitcnt vmcnt(4)
	v_lshlrev_b32_e32 v192, 16, v6
	v_and_b32_e32 v193, 0xffff0000, v6
	v_lshlrev_b32_e32 v194, 16, v7
	v_and_b32_e32 v195, 0xffff0000, v7
	v_lshlrev_b32_e32 v196, 16, v8
	v_and_b32_e32 v197, 0xffff0000, v8
	v_lshlrev_b32_e32 v198, 16, v9
	v_and_b32_e32 v199, 0xffff0000, v9
	s_waitcnt vmcnt(0)
	s_branch .LBB0_625

; #define IDX_LOAD(BUF, tl) do { const int tc_ = (tl) < 64 ? (tl) : 64; const unsigned char* bp_ = ws + WS_KI2 + ((size_t)b * 65 + tc_) * 4096 + (hh * 32 + lr) * 16; \
;                 _Pragma("unroll") for (int kk = 0; kk < 4; ++kk) BUF[kk] = *(const bf16x8*)(bp_ + kk * 1024); } while (0)
; __device__ __forceinline__ void phase_attn(const Params& P, unsigned char* lds) {
;     ...
;             IDX_LOAD(B0, 0); IDX_LOAD(B1, 1); IDX_LOAD(B2, 2); IDX_LOAD(B3, 3);
;             for (int tile = 0; tile < ntiles; tile += 4) {
;                 IDX_TILE(B0, tile);
;                 if (tile + 1 < ntiles) IDX_TILE(B1, tile + 1);
;                 if (tile + 2 < ntiles) IDX_TILE(B2, tile + 2);
;                 if (tile + 3 < ntiles) IDX_TILE(B3, tile + 3);
.LBB0_625:
	s_waitcnt vmcnt(15)
	v_mfma_f32_32x32x16_bf16 v[2:17], v[82:85], v[146:149], 0
	s_add_i32 s1, s0, 4
	s_min_u32 s6, s1, 64
	s_add_i32 s6, s6, s78
	s_lshl_b32 s30, s6, 12
	v_lshl_add_u64 v[230:231], v[166:167], 0, s[30:31]
	s_add_i32 s6, s0, 1
	s_cmp_ge_i32 s6, s38
	s_waitcnt vmcnt(14)
	v_mfma_f32_32x32x16_bf16 v[2:17], v[86:89], v[150:153], v[2:17]
	global_load_dwordx4 v[146:149], v[230:231], off
	global_load_dwordx4 v[150:153], v[230:231], off offset:1024
	s_waitcnt vmcnt(15)
	v_mfma_f32_32x32x16_bf16 v[2:17], v[90:93], v[154:157], v[2:17]
	s_waitcnt vmcnt(14)
	v_mfma_f32_32x32x16_bf16 v[2:17], v[94:97], v[158:161], v[2:17]
	global_load_dwordx4 v[154:157], v[230:231], off offset:2048
	global_load_dwordx4 v[158:161], v[230:231], off offset:3072
	s_nop 9
	v_max_i32_e32 v3, 0, v3
	v_max_i32_e32 v2, 0, v2
	v_pk_fma_f32 v[2:3], v[184:185], v[2:3], 0 op_sel_hi:[1,1,0]
	v_max_i32_e32 v5, 0, v5
	v_max_i32_e32 v4, 0, v4
	v_pk_fma_f32 v[2:3], v[186:187], v[4:5], v[2:3]
	v_max_i32_e32 v5, 0, v7
	v_max_i32_e32 v4, 0, v6
	v_pk_fma_f32 v[2:3], v[188:189], v[4:5], v[2:3]
	v_max_i32_e32 v5, 0, v9
	v_max_i32_e32 v4, 0, v8
	v_pk_fma_f32 v[2:3], v[190:191], v[4:5], v[2:3]
	v_max_i32_e32 v5, 0, v11
	v_max_i32_e32 v4, 0, v10
	v_pk_fma_f32 v[2:3], v[192:193], v[4:5], v[2:3]
	v_max_i32_e32 v5, 0, v13
	v_max_i32_e32 v4, 0, v12
	v_pk_fma_f32 v[2:3], v[194:195], v[4:5], v[2:3]
	v_max_i32_e32 v5, 0, v15
	v_max_i32_e32 v4, 0, v14
	v_pk_fma_f32 v[2:3], v[196:197], v[4:5], v[2:3]
	v_max_i32_e32 v5, 0, v17
	v_max_i32_e32 v4, 0, v16
	v_pk_fma_f32 v[2:3], v[198:199], v[4:5], v[2:3]
	s_nop 0
	v_pk_add_f32 v[2:3], v[2:3], v[2:3] op_sel:[1,0] op_sel_hi:[0,1]
	v_cmp_lt_i32_e32 vcc, -1, v2
	s_nop 1
	v_cndmask_b32_e32 v3, -1, v213, vcc
	v_xor_b32_e32 v2, v3, v2
	v_cmp_le_i32_e32 vcc, v226, v228
	s_nop 1
	v_cndmask_b32_e32 v2, 0, v2, vcc
	ds_write_b32 v227, v2
	s_cbranch_scc0 .LBB0_628
	s_cmp_ge_i32 s0, s72
	s_cbranch_scc0 .LBB0_629

; #define IDX_LOAD(BUF, tl) do { const int tc_ = (tl) < 64 ? (tl) : 64; const unsigned char* bp_ = ws + WS_KI2 + ((size_t)b * 65 + tc_) * 4096 + (hh * 32 + lr) * 16; \
;                 _Pragma("unroll") for (int kk = 0; kk < 4; ++kk) BUF[kk] = *(const bf16x8*)(bp_ + kk * 1024); } while (0)
; __device__ __forceinline__ void phase_attn(const Params& P, unsigned char* lds) {
;     ...
;             IDX_LOAD(B0, 0); IDX_LOAD(B1, 1); IDX_LOAD(B2, 2); IDX_LOAD(B3, 3);
;             for (int tile = 0; tile < ntiles; tile += 4) {
;                 IDX_TILE(B0, tile);
;                 if (tile + 1 < ntiles) IDX_TILE(B1, tile + 1);
;                 if (tile + 2 < ntiles) IDX_TILE(B2, tile + 2);
;                 if (tile + 3 < ntiles) IDX_TILE(B3, tile + 3);
.LBB0_628:
	s_waitcnt vmcnt(15)
	v_mfma_f32_32x32x16_bf16 v[2:17], v[82:85], v[134:137], 0
	s_min_u32 s6, s0, 59
	s_add_i32 s6, s83, s6
	s_lshl_b32 s30, s6, 12
	v_lshl_add_u64 v[230:231], v[166:167], 0, s[30:31]
	s_waitcnt vmcnt(14)
	v_mfma_f32_32x32x16_bf16 v[2:17], v[86:89], v[138:141], v[2:17]
	global_load_dwordx4 v[134:137], v[230:231], off
	global_load_dwordx4 v[138:141], v[230:231], off offset:1024
	s_waitcnt vmcnt(15)
	v_mfma_f32_32x32x16_bf16 v[2:17], v[90:93], v[142:145], v[2:17]
	s_waitcnt vmcnt(14)
	v_mfma_f32_32x32x16_bf16 v[2:17], v[94:97], v[114:117], v[2:17]
	global_load_dwordx4 v[142:145], v[230:231], off offset:2048
	global_load_dwordx4 v[114:117], v[230:231], off offset:3072
	s_nop 9
	v_max_i32_e32 v3, 0, v3
	v_max_i32_e32 v2, 0, v2
	v_pk_fma_f32 v[2:3], v[184:185], v[2:3], 0 op_sel_hi:[1,1,0]
	v_max_i32_e32 v5, 0, v5
	v_max_i32_e32 v4, 0, v4
	v_pk_fma_f32 v[2:3], v[186:187], v[4:5], v[2:3]
	v_max_i32_e32 v5, 0, v7
	v_max_i32_e32 v4, 0, v6
	v_pk_fma_f32 v[2:3], v[188:189], v[4:5], v[2:3]
	v_max_i32_e32 v5, 0, v9
	v_max_i32_e32 v4, 0, v8
	v_pk_fma_f32 v[2:3], v[190:191], v[4:5], v[2:3]
	v_max_i32_e32 v5, 0, v11
	v_max_i32_e32 v4, 0, v10
	v_pk_fma_f32 v[2:3], v[192:193], v[4:5], v[2:3]
	v_max_i32_e32 v5, 0, v13
	v_max_i32_e32 v4, 0, v12
	v_pk_fma_f32 v[2:3], v[194:195], v[4:5], v[2:3]
	v_max_i32_e32 v5, 0, v15
	v_max_i32_e32 v4, 0, v14
	v_pk_fma_f32 v[2:3], v[196:197], v[4:5], v[2:3]
	v_max_i32_e32 v5, 0, v17
	v_max_i32_e32 v4, 0, v16
	v_pk_fma_f32 v[2:3], v[198:199], v[4:5], v[2:3]
	v_add_u32_e32 v4, 32, v226
	v_pk_add_f32 v[2:3], v[2:3], v[2:3] op_sel:[1,0] op_sel_hi:[0,1]
	v_cmp_lt_i32_e32 vcc, -1, v2
	s_nop 1
	v_cndmask_b32_e32 v3, -1, v213, vcc
	v_xor_b32_e32 v2, v3, v2
	v_cmp_le_i32_e32 vcc, v4, v228
	s_nop 1
	v_cndmask_b32_e32 v2, 0, v2, vcc
	ds_write_b32 v227, v2 offset:128
	s_cmp_ge_i32 s0, s72
	s_cbranch_scc1 .LBB0_627
.LBB0_629:
	s_waitcnt vmcnt(15)
	v_mfma_f32_32x32x16_bf16 v[2:17], v[82:85], v[118:121], 0
	s_min_u32 s6, s0, 58
	s_add_i32 s6, s84, s6
	s_lshl_b32 s30, s6, 12
	v_lshl_add_u64 v[230:231], v[166:167], 0, s[30:31]
	s_waitcnt vmcnt(14)
	v_mfma_f32_32x32x16_bf16 v[2:17], v[86:89], v[110:113], v[2:17]
	global_load_dwordx4 v[118:121], v[230:231], off
	global_load_dwordx4 v[110:113], v[230:231], off offset:1024
	s_waitcnt vmcnt(15)
	v_mfma_f32_32x32x16_bf16 v[2:17], v[90:93], v[106:109], v[2:17]
	s_waitcnt vmcnt(14)
	v_mfma_f32_32x32x16_bf16 v[2:17], v[94:97], v[98:101], v[2:17]
	global_load_dwordx4 v[106:109], v[230:231], off offset:2048
	global_load_dwordx4 v[98:101], v[230:231], off offset:3072
	s_nop 9
	v_max_i32_e32 v3, 0, v3
	v_max_i32_e32 v2, 0, v2
	v_pk_fma_f32 v[2:3], v[184:185], v[2:3], 0 op_sel_hi:[1,1,0]
	v_max_i32_e32 v5, 0, v5
	v_max_i32_e32 v4, 0, v4
	v_pk_fma_f32 v[2:3], v[186:187], v[4:5], v[2:3]
	v_max_i32_e32 v5, 0, v7
	v_max_i32_e32 v4, 0, v6
	v_pk_fma_f32 v[2:3], v[188:189], v[4:5], v[2:3]
	v_max_i32_e32 v5, 0, v9
	v_max_i32_e32 v4, 0, v8
	v_pk_fma_f32 v[2:3], v[190:191], v[4:5], v[2:3]
	v_max_i32_e32 v5, 0, v11
	v_max_i32_e32 v4, 0, v10
	v_pk_fma_f32 v[2:3], v[192:193], v[4:5], v[2:3]
	v_max_i32_e32 v5, 0, v13
	v_max_i32_e32 v4, 0, v12
	v_pk_fma_f32 v[2:3], v[194:195], v[4:5], v[2:3]
	v_max_i32_e32 v5, 0, v15
	v_max_i32_e32 v4, 0, v14
	v_pk_fma_f32 v[2:3], v[196:197], v[4:5], v[2:3]
	v_max_i32_e32 v5, 0, v17
	v_max_i32_e32 v4, 0, v16
	v_pk_fma_f32 v[2:3], v[198:199], v[4:5], v[2:3]
	v_add_u32_e32 v4, 64, v226
	v_pk_add_f32 v[2:3], v[2:3], v[2:3] op_sel:[1,0] op_sel_hi:[0,1]
	v_cmp_lt_i32_e32 vcc, -1, v2
	s_nop 1
	v_cndmask_b32_e32 v3, -1, v213, vcc
	v_xor_b32_e32 v2, v3, v2
	v_cmp_le_i32_e32 vcc, v4, v228
	s_nop 1
	v_cndmask_b32_e32 v2, 0, v2, vcc
	ds_write_b32 v227, v2 offset:256
	s_add_i32 s6, s0, 3
	s_cmp_ge_i32 s6, s38
	s_cbranch_scc1 .LBB0_624
.LBB0_630:
	s_waitcnt vmcnt(15)
	v_mfma_f32_32x32x16_bf16 v[2:17], v[82:85], v[130:133], 0
	s_min_u32 s0, s0, 57
	s_add_i32 s0, s85, s0
	s_lshl_b32 s30, s0, 12
	v_lshl_add_u64 v[230:231], v[166:167], 0, s[30:31]
	s_waitcnt vmcnt(14)
	v_mfma_f32_32x32x16_bf16 v[2:17], v[86:89], v[126:129], v[2:17]
	global_load_dwordx4 v[130:133], v[230:231], off
	global_load_dwordx4 v[126:129], v[230:231], off offset:1024
	s_waitcnt vmcnt(15)
	v_mfma_f32_32x32x16_bf16 v[2:17], v[90:93], v[122:125], v[2:17]
	s_waitcnt vmcnt(14)
	v_mfma_f32_32x32x16_bf16 v[2:17], v[94:97], v[102:105], v[2:17]
	global_load_dwordx4 v[122:125], v[230:231], off offset:2048
	global_load_dwordx4 v[102:105], v[230:231], off offset:3072
	s_nop 9
	v_max_i32_e32 v3, 0, v3
	v_max_i32_e32 v2, 0, v2
	v_pk_fma_f32 v[2:3], v[184:185], v[2:3], 0 op_sel_hi:[1,1,0]
	v_max_i32_e32 v5, 0, v5
	v_max_i32_e32 v4, 0, v4
	v_pk_fma_f32 v[2:3], v[186:187], v[4:5], v[2:3]
	v_max_i32_e32 v5, 0, v7
	v_max_i32_e32 v4, 0, v6
	v_pk_fma_f32 v[2:3], v[188:189], v[4:5], v[2:3]
	v_max_i32_e32 v5, 0, v9
	v_max_i32_e32 v4, 0, v8
	v_pk_fma_f32 v[2:3], v[190:191], v[4:5], v[2:3]
	v_max_i32_e32 v5, 0, v11
	v_max_i32_e32 v4, 0, v10
	v_pk_fma_f32 v[2:3], v[192:193], v[4:5], v[2:3]
	v_max_i32_e32 v5, 0, v13
	v_max_i32_e32 v4, 0, v12
	v_pk_fma_f32 v[2:3], v[194:195], v[4:5], v[2:3]
	v_max_i32_e32 v5, 0, v15
	v_max_i32_e32 v4, 0, v14
	v_pk_fma_f32 v[2:3], v[196:197], v[4:5], v[2:3]
	v_max_i32_e32 v5, 0, v17
	v_max_i32_e32 v4, 0, v16
	v_pk_fma_f32 v[2:3], v[198:199], v[4:5], v[2:3]
	v_add_u32_e32 v4, 0x60, v226
	v_pk_add_f32 v[2:3], v[2:3], v[2:3] op_sel:[0,1] op_sel_hi:[1,0]
	s_nop 0
	v_cmp_lt_i32_e32 vcc, -1, v2
	s_nop 1
	v_cndmask_b32_e32 v3, -1, v213, vcc
	v_xor_b32_e32 v2, v3, v2
	v_cmp_le_i32_e32 vcc, v4, v228
	s_nop 1
	v_cndmask_b32_e32 v2, 0, v2, vcc
	ds_write_b32 v227, v2 offset:384
	s_branch .LBB0_624
